# attention S block: counted lgkmcnt waits at each MFMA's first consumer instead of one lgkmcnt(0)
# baseline (speedup 1.0000x reference)
; #define LAS __attribute__((address_space(3)))
; __device__ __forceinline__ int crow(int reg, int h) { return (reg & 3) + 8 * (reg >> 2) + 4 * h; }
; #define MFMA32(a, b, c) __builtin_amdgcn_mfma_f32_32x32x16_bf16((a), (b), (c), 0, 0, 0)
; template <bool DIFF> ...
;     ...
;             for (int ks = 0; ks < KS; ++ks) {
;                 const bf16x8 a0 = *(const LAS bf16x8*)(kbuf + r * 272 + (ks * 16 + h * 8) * 2);
;                 const bf16x8 a1 = *(const LAS bf16x8*)(kbuf + (32 + r) * 272 + (ks * 16 + h * 8) * 2);
;                 s0 = MFMA32(a0, bq[ks], s0); s1 = MFMA32(a1, bq[ks], s1);
;             }
;             if (t * 64 + 64 > nkeys) {
; #pragma unroll
;                 for (int ii = 0; ii < 16; ++ii) { const int key = t * 64 + crow(ii, h); if (key >= nkeys) s0[ii] = -INFINITY; if (key + 32 >= nkeys) s1[ii] = -INFINITY; }
;             }
.LBB0_1482:
	s_bitcmp0_b32 s15, 0
	s_cbranch_scc1 .LBB0_1493
	s_cmp_le_u32 s0, s1
	s_waitcnt lgkmcnt(7)
	v_mfma_f32_32x32x16_bf16 v[112:127], v[2:5], v[128:131], v[80:95]
	s_waitcnt lgkmcnt(6)
	v_mfma_f32_32x32x16_bf16 v[96:111], v[10:13], v[128:131], v[80:95]
	s_waitcnt lgkmcnt(5)
	v_mfma_f32_32x32x16_bf16 v[112:127], v[6:9], v[132:135], v[112:127]
	s_waitcnt lgkmcnt(4)
	v_mfma_f32_32x32x16_bf16 v[96:111], v[212:215], v[132:135], v[96:111]
	s_waitcnt lgkmcnt(3)
	v_mfma_f32_32x32x16_bf16 v[112:127], v[216:219], v[136:139], v[112:127]
	s_waitcnt lgkmcnt(2)
	v_mfma_f32_32x32x16_bf16 v[96:111], v[224:227], v[136:139], v[96:111]
	s_waitcnt lgkmcnt(1)
	v_mfma_f32_32x32x16_bf16 v[112:127], v[220:223], v[140:143], v[112:127]
	s_waitcnt lgkmcnt(0)
	v_mfma_f32_32x32x16_bf16 v[96:111], v[228:231], v[140:143], v[96:111]
	s_cbranch_scc1 .LBB0_1485
	v_add_u32_e32 v0, s0, v177
	v_add_u32_e32 v2, 32, v0
	v_cmp_gt_u32_e32 vcc, s81, v2
	v_add_u32_e32 v2, 1, v0
	v_cmp_gt_u32_e64 s[44:45], s81, v2
	v_add_u32_e32 v2, 33, v0
	v_cmp_gt_u32_e64 s[14:15], s81, v2
	v_add_u32_e32 v2, 2, v0
	v_cmp_gt_u32_e64 s[48:49], s81, v2
	v_add_u32_e32 v2, 34, v0
	v_cmp_gt_u32_e64 s[16:17], s81, v2
	v_add_u32_e32 v2, 3, v0
	v_cmp_gt_u32_e64 s[50:51], s81, v2
	v_add_u32_e32 v2, 35, v0
	v_cmp_gt_u32_e64 s[18:19], s81, v2
	v_add_u32_e32 v2, 8, v0
	v_cmp_gt_u32_e64 s[52:53], s81, v2
	v_add_u32_e32 v2, 40, v0
	v_cmp_gt_u32_e64 s[20:21], s81, v2
	v_add_u32_e32 v2, 9, v0
	v_cmp_gt_u32_e64 s[54:55], s81, v2
	v_add_u32_e32 v2, 41, v0
	v_cmp_gt_u32_e64 s[22:23], s81, v2
	v_add_u32_e32 v2, 10, v0
	v_cmp_gt_u32_e64 s[56:57], s81, v2
	v_add_u32_e32 v2, 42, v0
	v_cmp_gt_u32_e64 s[24:25], s81, v2
	v_add_u32_e32 v2, 11, v0
	v_cmp_gt_u32_e64 s[58:59], s81, v2
	v_add_u32_e32 v2, 43, v0
	v_cmp_gt_u32_e64 s[26:27], s81, v2
	v_add_u32_e32 v2, 16, v0
	v_cmp_gt_u32_e64 s[60:61], s81, v2
	v_add_u32_e32 v2, 48, v0
	v_cmp_gt_u32_e64 s[28:29], s81, v2
	v_add_u32_e32 v2, 17, v0
	v_cmp_gt_u32_e64 s[62:63], s81, v2
	v_add_u32_e32 v2, 49, v0
	v_cmp_gt_u32_e64 s[30:31], s81, v2
	v_add_u32_e32 v2, 18, v0
	v_cmp_gt_u32_e64 s[64:65], s81, v2
	v_add_u32_e32 v2, 50, v0
	v_cmp_gt_u32_e64 s[34:35], s81, v2
	v_add_u32_e32 v2, 19, v0
	v_cmp_gt_u32_e64 s[66:67], s81, v2
	v_add_u32_e32 v2, 51, v0
	v_cmp_gt_u32_e64 s[36:37], s81, v2
	v_add_u32_e32 v2, 24, v0
	v_cmp_gt_u32_e64 s[68:69], s81, v2
	v_add_u32_e32 v2, 56, v0
	v_cmp_gt_u32_e64 s[38:39], s81, v2
	v_add_u32_e32 v2, 25, v0
	v_cmp_gt_u32_e64 s[70:71], s81, v2
	v_add_u32_e32 v2, 57, v0
	v_cmp_gt_u32_e64 s[42:43], s81, v2
	v_add_u32_e32 v2, 26, v0
	v_cmp_gt_u32_e64 s[72:73], s81, v2
	v_add_u32_e32 v2, 58, v0
	v_cmp_gt_u32_e64 s[46:47], s81, v2
	v_add_u32_e32 v2, 27, v0
	v_cmp_gt_u32_e64 s[74:75], s81, v2
	s_or_b64 s[72:73], s[74:75], s[72:73]
	s_or_b64 s[70:71], s[72:73], s[70:71]
	s_or_b64 s[68:69], s[70:71], s[68:69]
	s_or_b64 s[66:67], s[68:69], s[66:67]
	s_or_b64 s[64:65], s[66:67], s[64:65]
	s_or_b64 s[62:63], s[64:65], s[62:63]
	s_or_b64 s[60:61], s[62:63], s[60:61]
	s_or_b64 s[58:59], s[60:61], s[58:59]
	s_or_b64 s[56:57], s[58:59], s[56:57]
	s_or_b64 s[54:55], s[56:57], s[54:55]
	s_or_b64 s[52:53], s[54:55], s[52:53]
	s_or_b64 s[50:51], s[52:53], s[50:51]
	s_or_b64 s[48:49], s[50:51], s[48:49]
	v_cmp_gt_u32_e64 s[40:41], s81, v0
	s_or_b64 s[44:45], s[48:49], s[44:45]
	s_or_b64 s[40:41], s[44:45], s[40:41]
	v_add_u32_e32 v0, 59, v0
	v_cndmask_b32_e64 v112, v211, v112, s[40:41]
	v_cmp_gt_u32_e64 s[40:41], s81, v0
	v_cndmask_b32_e64 v127, v211, v127, s[74:75]
	v_cndmask_b32_e64 v126, v211, v126, s[72:73]
	v_cndmask_b32_e64 v111, v211, v111, s[40:41]
	s_or_b64 s[40:41], s[40:41], s[46:47]
	v_cndmask_b32_e64 v110, v211, v110, s[40:41]
	s_or_b64 s[40:41], s[40:41], s[42:43]
	s_or_b64 s[38:39], s[40:41], s[38:39]
	s_or_b64 s[36:37], s[38:39], s[36:37]
	s_or_b64 s[34:35], s[36:37], s[34:35]
	s_or_b64 s[30:31], s[34:35], s[30:31]
	s_or_b64 s[28:29], s[30:31], s[28:29]
	s_or_b64 s[26:27], s[28:29], s[26:27]
	s_or_b64 s[24:25], s[26:27], s[24:25]
	s_or_b64 s[22:23], s[24:25], s[22:23]
	s_or_b64 s[20:21], s[22:23], s[20:21]
	s_or_b64 s[18:19], s[20:21], s[18:19]
	s_or_b64 s[16:17], s[18:19], s[16:17]
	s_or_b64 s[14:15], s[16:17], s[14:15]
	s_or_b64 vcc, s[14:15], vcc
	v_cndmask_b32_e64 v125, v211, v125, s[70:71]
	v_cndmask_b32_e64 v124, v211, v124, s[68:69]
	v_cndmask_b32_e64 v123, v211, v123, s[66:67]
	v_cndmask_b32_e64 v122, v211, v122, s[64:65]
	v_cndmask_b32_e64 v121, v211, v121, s[62:63]
	v_cndmask_b32_e64 v120, v211, v120, s[60:61]
	v_cndmask_b32_e64 v119, v211, v119, s[58:59]
	v_cndmask_b32_e64 v118, v211, v118, s[56:57]
	v_cndmask_b32_e64 v117, v211, v117, s[54:55]
	v_cndmask_b32_e64 v116, v211, v116, s[52:53]
	v_cndmask_b32_e64 v115, v211, v115, s[50:51]
	v_cndmask_b32_e64 v114, v211, v114, s[48:49]
	v_cndmask_b32_e64 v113, v211, v113, s[44:45]
	v_cndmask_b32_e64 v109, v211, v109, s[40:41]
	v_cndmask_b32_e64 v108, v211, v108, s[38:39]
	v_cndmask_b32_e64 v107, v211, v107, s[36:37]
	v_cndmask_b32_e64 v106, v211, v106, s[34:35]
	v_cndmask_b32_e64 v105, v211, v105, s[30:31]
	v_cndmask_b32_e64 v104, v211, v104, s[28:29]
	v_cndmask_b32_e64 v103, v211, v103, s[26:27]
	v_cndmask_b32_e64 v102, v211, v102, s[24:25]
	v_cndmask_b32_e64 v101, v211, v101, s[22:23]
	v_cndmask_b32_e64 v100, v211, v100, s[20:21]
	v_cndmask_b32_e64 v99, v211, v99, s[18:19]
	v_cndmask_b32_e64 v98, v211, v98, s[16:17]
	v_cndmask_b32_e64 v97, v211, v97, s[14:15]
	v_cndmask_b32_e32 v96, v211, v96, vcc
